# v55 + RWKV solve start waits only for its own early reads (lgkmcnt(11)), not for the staging writes issued after them
# baseline (speedup 1.0000x reference)
; #define LAS __attribute__((address_space(3)))
; __device__ __forceinline__ unsigned pk2(float lo, float hi) { const bf2_t r = __builtin_convertvector((f32x2){lo, hi}, bf2_t); unsigned u; __builtin_memcpy(&u, &r, 4); return u; }
; __device__ __forceinline__ void rwkv_chunk_item(const P& p, const Ctx& c, int seg, int w, bool save) {
;     ...
;         if (c.wv == 0) {
;             float u[16];
; #pragma unroll
;             for (int p2 = 0; p2 < 8; ++p2) { f32x2 acc = (f32x2){XF[c.lane * 17 + 2 * p2], XF[c.lane * 17 + 2 * p2 + 1]};
; #pragma unroll
;                 for (int s2 = 0; s2 < 2 * p2; ++s2) { const f32x2 m = *(const LAS f32x2*)(MABT + s2 * 20 + 2 * p2); acc += (f32x2){u[s2], u[s2]} * m; }
;                 u[2 * p2] = acc.x;
;                 u[2 * p2 + 1] = acc.y + acc.x * MABT[(2 * p2) * 20 + 2 * p2 + 1]; }
;             *(LAS u32x4*)(UV + c.lane * 40) = (u32x4){pk2(u[0], u[1]), pk2(u[2], u[3]), pk2(u[4], u[5]), pk2(u[6], u[7])};
;             *(LAS u32x4*)(UV + c.lane * 40 + 8) = (u32x4){pk2(u[8], u[9]), pk2(u[10], u[11]), pk2(u[12], u[13]), pk2(u[14], u[15])};
;         }
.LBB0_895:
	s_waitcnt lgkmcnt(11)
	v_fma_f32 v46, v170, v100, v101
	v_pk_fma_f32 v[102:103], v[100:101], v[156:157], v[102:103] op_sel_hi:[0,1,1]
	v_pk_fma_f32 v[52:53], v[100:101], v[230:231], v[52:53] op_sel_hi:[0,1,1]
	v_pk_fma_f32 v[56:57], v[100:101], v[232:233], v[56:57] op_sel_hi:[0,1,1]
	v_pk_fma_f32 v[60:61], v[100:101], v[124:125], v[60:61] op_sel_hi:[0,1,1]
	v_pk_fma_f32 v[64:65], v[100:101], v[126:127], v[64:65] op_sel_hi:[0,1,1]
	v_pk_fma_f32 v[68:69], v[100:101], v[176:177], v[68:69] op_sel_hi:[0,1,1]
	v_pk_fma_f32 v[72:73], v[100:101], v[178:179], v[72:73] op_sel_hi:[0,1,1]
	v_pk_fma_f32 v[102:103], v[46:47], v[158:159], v[102:103] op_sel_hi:[0,1,1]
	v_pk_fma_f32 v[52:53], v[46:47], v[234:235], v[52:53] op_sel_hi:[0,1,1]
	v_pk_fma_f32 v[56:57], v[46:47], v[236:237], v[56:57] op_sel_hi:[0,1,1]
	v_pk_fma_f32 v[60:61], v[46:47], v[128:129], v[60:61] op_sel_hi:[0,1,1]
	v_pk_fma_f32 v[64:65], v[46:47], v[130:131], v[64:65] op_sel_hi:[0,1,1]
	v_pk_fma_f32 v[68:69], v[46:47], v[180:181], v[68:69] op_sel_hi:[0,1,1]
	v_pk_fma_f32 v[72:73], v[46:47], v[182:183], v[72:73] op_sel_hi:[0,1,1]
	ds_read_b32 v173, v253 offset:22356
	ds_read_b64 v[160:161], v253 offset:22360
	ds_read_b128 v[140:143], v253 offset:22368
	ds_read_b128 v[192:195], v253 offset:22384
	ds_read_b64 v[162:163], v253 offset:22440
	ds_read_b128 v[144:147], v253 offset:22448
	ds_read_b128 v[196:199], v253 offset:22464
	s_waitcnt lgkmcnt(7)
	v_fma_f32 v50, v172, v102, v103
	v_pk_fma_f32 v[52:53], v[102:103], v[238:239], v[52:53] op_sel_hi:[0,1,1]
	v_pk_fma_f32 v[56:57], v[102:103], v[240:241], v[56:57] op_sel_hi:[0,1,1]
	v_pk_fma_f32 v[60:61], v[102:103], v[132:133], v[60:61] op_sel_hi:[0,1,1]
	v_pk_fma_f32 v[64:65], v[102:103], v[134:135], v[64:65] op_sel_hi:[0,1,1]
	v_pk_fma_f32 v[68:69], v[102:103], v[184:185], v[68:69] op_sel_hi:[0,1,1]
	v_pk_fma_f32 v[72:73], v[102:103], v[186:187], v[72:73] op_sel_hi:[0,1,1]
	v_pk_fma_f32 v[52:53], v[50:51], v[242:243], v[52:53] op_sel_hi:[0,1,1]
	v_pk_fma_f32 v[56:57], v[50:51], v[244:245], v[56:57] op_sel_hi:[0,1,1]
	v_pk_fma_f32 v[60:61], v[50:51], v[136:137], v[60:61] op_sel_hi:[0,1,1]
	v_pk_fma_f32 v[64:65], v[50:51], v[138:139], v[64:65] op_sel_hi:[0,1,1]
	v_pk_fma_f32 v[68:69], v[50:51], v[188:189], v[68:69] op_sel_hi:[0,1,1]
	v_pk_fma_f32 v[72:73], v[50:51], v[190:191], v[72:73] op_sel_hi:[0,1,1]
	ds_read_b32 v174, v253 offset:22524
	ds_read_b128 v[148:151], v253 offset:22528
	ds_read_b128 v[200:203], v253 offset:22544
	ds_read_b128 v[152:155], v253 offset:22608
	ds_read_b128 v[204:207], v253 offset:22624
	s_waitcnt lgkmcnt(5)
	v_fma_f32 v54, v173, v52, v53
	v_pk_fma_f32 v[56:57], v[52:53], v[160:161], v[56:57] op_sel_hi:[0,1,1]
	v_pk_fma_f32 v[60:61], v[52:53], v[140:141], v[60:61] op_sel_hi:[0,1,1]
	v_pk_fma_f32 v[64:65], v[52:53], v[142:143], v[64:65] op_sel_hi:[0,1,1]
	v_pk_fma_f32 v[68:69], v[52:53], v[192:193], v[68:69] op_sel_hi:[0,1,1]
	v_pk_fma_f32 v[72:73], v[52:53], v[194:195], v[72:73] op_sel_hi:[0,1,1]
	v_pk_fma_f32 v[56:57], v[54:55], v[162:163], v[56:57] op_sel_hi:[0,1,1]
	v_pk_fma_f32 v[60:61], v[54:55], v[144:145], v[60:61] op_sel_hi:[0,1,1]
	v_pk_fma_f32 v[64:65], v[54:55], v[146:147], v[64:65] op_sel_hi:[0,1,1]
	v_pk_fma_f32 v[68:69], v[54:55], v[196:197], v[68:69] op_sel_hi:[0,1,1]
	v_pk_fma_f32 v[72:73], v[54:55], v[198:199], v[72:73] op_sel_hi:[0,1,1]
	ds_read_b32 v248, v253 offset:22692
	ds_read_b64 v[164:165], v253 offset:22696
	ds_read_b128 v[208:211], v253 offset:22704
	ds_read_b64 v[166:167], v253 offset:22776
	ds_read_b128 v[218:221], v253 offset:22784
	s_waitcnt lgkmcnt(5)
	v_fma_f32 v58, v174, v56, v57
	v_pk_fma_f32 v[60:61], v[56:57], v[148:149], v[60:61] op_sel_hi:[0,1,1]
	v_pk_fma_f32 v[64:65], v[56:57], v[150:151], v[64:65] op_sel_hi:[0,1,1]
	v_pk_fma_f32 v[68:69], v[56:57], v[200:201], v[68:69] op_sel_hi:[0,1,1]
	v_pk_fma_f32 v[72:73], v[56:57], v[202:203], v[72:73] op_sel_hi:[0,1,1]
	v_pk_fma_f32 v[60:61], v[58:59], v[152:153], v[60:61] op_sel_hi:[0,1,1]
	v_pk_fma_f32 v[64:65], v[58:59], v[154:155], v[64:65] op_sel_hi:[0,1,1]
	v_pk_fma_f32 v[68:69], v[58:59], v[204:205], v[68:69] op_sel_hi:[0,1,1]
	v_pk_fma_f32 v[72:73], v[58:59], v[206:207], v[72:73] op_sel_hi:[0,1,1]
	ds_read_b32 v249, v253 offset:22860
	ds_read_b128 v[222:225], v253 offset:22864
	ds_read_b128 v[226:229], v253 offset:22944
	s_waitcnt lgkmcnt(3)
	v_fma_f32 v62, v248, v60, v61
	v_pk_fma_f32 v[64:65], v[60:61], v[164:165], v[64:65] op_sel_hi:[0,1,1]
	v_pk_fma_f32 v[68:69], v[60:61], v[208:209], v[68:69] op_sel_hi:[0,1,1]
	v_pk_fma_f32 v[72:73], v[60:61], v[210:211], v[72:73] op_sel_hi:[0,1,1]
	v_pk_fma_f32 v[64:65], v[62:63], v[166:167], v[64:65] op_sel_hi:[0,1,1]
	v_pk_fma_f32 v[68:69], v[62:63], v[218:219], v[68:69] op_sel_hi:[0,1,1]
	v_pk_fma_f32 v[72:73], v[62:63], v[220:221], v[72:73] op_sel_hi:[0,1,1]
	ds_read_b32 v250, v253 offset:23028
	ds_read_b64 v[168:169], v253 offset:23032
	ds_read_b64 v[246:247], v253 offset:23112
	s_waitcnt lgkmcnt(3)
	v_fma_f32 v66, v249, v64, v65
	v_pk_fma_f32 v[68:69], v[64:65], v[222:223], v[68:69] op_sel_hi:[0,1,1]
	v_pk_fma_f32 v[72:73], v[64:65], v[224:225], v[72:73] op_sel_hi:[0,1,1]
	v_pk_fma_f32 v[68:69], v[66:67], v[226:227], v[68:69] op_sel_hi:[0,1,1]
	v_pk_fma_f32 v[72:73], v[66:67], v[228:229], v[72:73] op_sel_hi:[0,1,1]
	ds_read_b32 v251, v253 offset:23196
	s_waitcnt lgkmcnt(1)
	v_fma_f32 v120, v250, v68, v69
	v_pk_fma_f32 v[72:73], v[68:69], v[168:169], v[72:73] op_sel_hi:[0,1,1]
	v_pk_fma_f32 v[72:73], v[120:121], v[246:247], v[72:73] op_sel_hi:[0,1,1]
	s_waitcnt lgkmcnt(0)
	v_fma_f32 v122, v251, v72, v73
	v_add_u32_e32 v252, s88, v80
	v_cvt_pk_bf16_f32 v44, v100, v46
	v_cvt_pk_bf16_f32 v45, v102, v50
	v_cvt_pk_bf16_f32 v46, v52, v54
	v_cvt_pk_bf16_f32 v47, v56, v58
	ds_write_b128 v252, v[44:47] offset:14336
	v_cvt_pk_bf16_f32 v44, v60, v62
	v_cvt_pk_bf16_f32 v45, v64, v66
	v_cvt_pk_bf16_f32 v46, v68, v120
	v_cvt_pk_bf16_f32 v47, v72, v122
	ds_write_b128 v252, v[44:47] offset:14352
	s_setprio 0
